# conv phase two-deep load pipeline: the four batch steps per line fully unrolled, two alternating 32-VGPR sets with their own mask SGPRs, prefetch across the line boundary; unit order v2b
# speedup vs baseline: 1.0322x; 1.0035x over previous
;     __device__ bool next(int i, Unit& u) const { const long L = (long)i * G + c; if (L >= nwg) return false; return map((int)L, u); }
;     __device__ bool next(int i, Unit& u) const {
;         const long L = (long)i * G + c;
;         if (L < nwg) return map((int)L, u);
;         const int k = (int)(L - nwg); if (k >= 64) return false;
;         u.pm = 128 + (k >> 3); u.pn = k & 7; return true;
.Lp2_map_a3:
	s_lshl_b32 s50, s11, 2
	s_lshl_b32 s64, s86, 1
	s_add_u32 s50, s50, s64
	s_sub_u32 s50, s50, 3
	s_sub_u32 s51, s86, 4
	s_branch .Lp2_map_fin

;     __device__ bool next(int i, Unit& u) const { const long L = (long)i * G + c; if (L >= nwg) return false; return map((int)L, u); }
;     __device__ bool next(int i, Unit& u) const {
;         const long L = (long)i * G + c;
;         if (L < nwg) return map((int)L, u);
;         const int k = (int)(L - nwg); if (k >= 64) return false;
;         u.pm = 128 + (k >> 3); u.pn = k & 7; return true;
.Lp2_map_c:
	s_cmp_lg_u32 s86, 6
	s_cbranch_scc1 .Lp2_map_c7
	s_and_b32 s64, s11, 1
	s_cmp_lg_u32 s64, 0
	s_cbranch_scc1 .Lp2_map_fin
	s_mov_b32 s51, 3
	s_branch .Lp2_map_fin

; #define LAS __attribute__((address_space(3)))
; __device__ __forceinline__ float bf_lo(unsigned u) { return __uint_as_float(u << 16); }
; __device__ __forceinline__ float bf_hi(unsigned u) { return __uint_as_float(u & 0xffff0000u); }
; __device__ void conv_phase(LAS unsigned char* lds, const Params& p) {
;     ...
;         for (int line = 0; line < 2; ++line) {
;             const int tok0 = half ? (c0 + line) : (r0 + line) * 64;
;             const unsigned offb = (unsigned)((b * 4096 + tok0) * 512 + ch0) * 2u;
;             asm volatile("" ::: "memory");
;             float cur[2][8];
; #pragma unroll
;             for (int a = 0; a < 2; ++a)
; #pragma unroll
;                 for (int c = 0; c < 8; ++c) cur[a][c] = 0.f;
;             float Wp[8];
; #pragma unroll
;             for (int c = 0; c < 8; ++c) Wp[c] = 0.f;
; #pragma unroll 1
;             for (int hb = 0; hb < 4; ++hb) {
;                 u32x4 raw[8];
; #pragma unroll
;                 for (int q = 0; q < 8; ++q) {
;                     const int xx = base - 15 + hb * 8 + q;
;                     const int xc = min(max(xx, 0), 63);
;                     const u32x4 r = *(const u32x4*)(Pb + (offb + (unsigned)xc * stepB));
;                     const bool ok = (xx == xc);
;                     raw[q] = (u32x4){ok ? r[0] : 0u, ok ? r[1] : 0u, ok ? r[2] : 0u, ok ? r[3] : 0u};
;                 }
;                 const LAS float* wrow = wl + hb * 8 * 512 + ch0;
; #pragma unroll
;                 for (int q = 0; q < 8; ++q) {
;                     const float in[8] = {bf_lo(raw[q][0]), bf_hi(raw[q][0]), bf_lo(raw[q][1]), bf_hi(raw[q][1]), bf_lo(raw[q][2]), bf_hi(raw[q][2]), bf_lo(raw[q][3]), bf_hi(raw[q][3])};
;                     const f32x4 wa = *(const LAS f32x4*)(wrow + q * 512), wb = *(const LAS f32x4*)(wrow + q * 512 + 4);
;                     const float Wc[8] = {wa[0], wa[1], wa[2], wa[3], wb[0], wb[1], wb[2], wb[3]};
.LBB0_373:
	v_or_b32_e32 v3, s10, v124
	v_or_b32_e32 v2, s10, v123
	v_lshlrev_b32_e32 v3, 6, v3
	v_cndmask_b32_e64 v2, v2, v3, s[6:7]
	v_mov_b32_e32 v107, 0
	s_xor_b64 s[38:39], s[8:9], -1
	v_lshl_or_b32 v126, v2, 10, v125
	s_mov_b32 s41, 0
	v_mov_b32_e32 v127, v119
	v_mov_b32_e32 v106, v107
	v_mov_b32_e32 v109, v107
	v_mov_b32_e32 v108, v107
	v_mov_b32_e32 v111, v107
	v_mov_b32_e32 v110, v107
	v_mov_b32_e32 v34, v107
	v_mov_b32_e32 v35, v107
	v_mov_b32_e32 v4, v107
	v_mov_b32_e32 v5, v107
	v_mov_b32_e32 v113, v107
	v_mov_b32_e32 v112, v107
	v_mov_b32_e32 v100, v107
	v_mov_b32_e32 v101, v107
	v_mov_b32_e32 v2, v107
	v_mov_b32_e32 v3, v107
	v_mov_b32_e32 v102, v107
	v_mov_b32_e32 v103, v107
	v_mov_b32_e32 v8, v107
	v_mov_b32_e32 v9, v107
	v_mov_b32_e32 v104, v107
	v_mov_b32_e32 v105, v107
	v_mov_b32_e32 v6, v107
	v_mov_b32_e32 v7, v107
	s_cmp_lg_u32 s10, 0
	s_cbranch_scc1 .Lp4_pre_done
	v_add_u32_e32 v193, -15, v115
	v_med3_i32 v194, v193, 0, 63
	v_cmp_eq_u32_e64 s[76:77], v193, v194
	v_lshl_add_u32 v192, v194, v118, v126
	v_add_u32_e32 v197, -14, v115
	v_med3_i32 v198, v197, 0, 63
	v_cmp_eq_u32_e64 s[78:79], v197, v198
	v_lshl_add_u32 v196, v198, v118, v126
	v_add_u32_e32 v201, -13, v115
	v_med3_i32 v202, v201, 0, 63
	v_cmp_eq_u32_e64 s[80:81], v201, v202
	v_lshl_add_u32 v200, v202, v118, v126
	v_add_u32_e32 v205, -12, v115
	v_med3_i32 v206, v205, 0, 63
	v_cmp_eq_u32_e64 s[82:83], v205, v206
	v_lshl_add_u32 v204, v206, v118, v126
	v_add_u32_e32 v209, -11, v115
	v_med3_i32 v210, v209, 0, 63
	v_cmp_eq_u32_e64 s[84:85], v209, v210
	v_lshl_add_u32 v208, v210, v118, v126
	v_add_u32_e32 v213, -10, v115
	v_med3_i32 v214, v213, 0, 63
	v_cmp_eq_u32_e64 s[88:89], v213, v214
	v_lshl_add_u32 v212, v214, v118, v126
	v_add_u32_e32 v217, -9, v115
	v_med3_i32 v218, v217, 0, 63
	v_cmp_eq_u32_e64 s[90:91], v217, v218
	v_lshl_add_u32 v216, v218, v118, v126
	v_add_u32_e32 v221, -8, v115
	v_med3_i32 v222, v221, 0, 63
	v_cmp_eq_u32_e64 s[92:93], v221, v222
	v_lshl_add_u32 v220, v222, v118, v126
	global_load_dwordx4 v[192:195], v192, s[26:27]
	s_nop 0
	global_load_dwordx4 v[196:199], v196, s[26:27]
	s_nop 0
	global_load_dwordx4 v[200:203], v200, s[26:27]
	s_nop 0
	global_load_dwordx4 v[204:207], v204, s[26:27]
	s_nop 0
	global_load_dwordx4 v[208:211], v208, s[26:27]
	s_nop 0
	global_load_dwordx4 v[212:215], v212, s[26:27]
	s_nop 0
	global_load_dwordx4 v[216:219], v216, s[26:27]
	s_nop 0
	global_load_dwordx4 v[220:223], v220, s[26:27]
	v_add_u32_e32 v225, -7, v115
	v_med3_i32 v226, v225, 0, 63
	v_cmp_eq_u32_e64 s[42:43], v225, v226
	v_lshl_add_u32 v224, v226, v118, v126
	v_add_u32_e32 v229, -6, v115
	v_med3_i32 v230, v229, 0, 63
	v_cmp_eq_u32_e64 s[44:45], v229, v230
	v_lshl_add_u32 v228, v230, v118, v126
	v_add_u32_e32 v233, -5, v115
	v_med3_i32 v234, v233, 0, 63
	v_cmp_eq_u32_e64 s[46:47], v233, v234
	v_lshl_add_u32 v232, v234, v118, v126
	v_add_u32_e32 v237, -4, v115
	v_med3_i32 v238, v237, 0, 63
	v_cmp_eq_u32_e64 s[50:51], v237, v238
	v_lshl_add_u32 v236, v238, v118, v126
	v_add_u32_e32 v241, -3, v115
	v_med3_i32 v242, v241, 0, 63
	v_cmp_eq_u32_e64 s[52:53], v241, v242
	v_lshl_add_u32 v240, v242, v118, v126
	v_add_u32_e32 v245, -2, v115
	v_med3_i32 v246, v245, 0, 63
	v_cmp_eq_u32_e64 s[64:65], v245, v246
	v_lshl_add_u32 v244, v246, v118, v126
	v_add_u32_e32 v249, -1, v115
	v_med3_i32 v250, v249, 0, 63
	v_cmp_eq_u32_e64 s[94:95], v249, v250
	v_lshl_add_u32 v248, v250, v118, v126
	v_add_u32_e32 v253, 0, v115
	v_med3_i32 v254, v253, 0, 63
	v_cmp_eq_u32_e64 s[96:97], v253, v254
	v_lshl_add_u32 v252, v254, v118, v126
	global_load_dwordx4 v[224:227], v224, s[26:27]
	s_nop 0
	global_load_dwordx4 v[228:231], v228, s[26:27]
	s_nop 0
	global_load_dwordx4 v[232:235], v232, s[26:27]
	s_nop 0
	global_load_dwordx4 v[236:239], v236, s[26:27]
	s_nop 0
	global_load_dwordx4 v[240:243], v240, s[26:27]
	s_nop 0
	global_load_dwordx4 v[244:247], v244, s[26:27]
	s_nop 0
	global_load_dwordx4 v[248:251], v248, s[26:27]
	s_nop 0
	global_load_dwordx4 v[252:255], v252, s[26:27]
.Lp4_pre_done:
.Lp4_steps:
	ds_read_b128 v[14:17], v127
	ds_read_b128 v[10:13], v127 offset:16
	v_mov_b32_e32 v116, v35
	v_mov_b32_e32 v117, v34
	ds_read_b128 v[22:25], v127 offset:2048
	ds_read_b128 v[18:21], v127 offset:2064
	ds_read_b128 v[30:33], v127 offset:4096
	ds_read_b128 v[26:29], v127 offset:4112
	ds_read_b128 v[38:41], v127 offset:6144
	ds_read_b128 v[34:37], v127 offset:6160
	ds_read_b128 v[46:49], v127 offset:8192
	ds_read_b128 v[42:45], v127 offset:8208
	ds_read_b128 v[54:57], v127 offset:10240
	ds_read_b128 v[50:53], v127 offset:10256
	ds_read_b128 v[62:65], v127 offset:12288
	ds_read_b128 v[58:61], v127 offset:12304
	s_waitcnt vmcnt(15)
	v_cndmask_b32_e64 v160, 0, v192, s[76:77]
	v_cndmask_b32_e64 v161, 0, v193, s[76:77]
	v_cndmask_b32_e64 v162, 0, v194, s[76:77]
	v_cndmask_b32_e64 v163, 0, v195, s[76:77]
	s_waitcnt vmcnt(14)
	v_cndmask_b32_e64 v164, 0, v196, s[78:79]
	v_cndmask_b32_e64 v165, 0, v197, s[78:79]
	v_cndmask_b32_e64 v166, 0, v198, s[78:79]
	v_cndmask_b32_e64 v167, 0, v199, s[78:79]
	s_waitcnt vmcnt(13)
	v_cndmask_b32_e64 v168, 0, v200, s[80:81]
	v_cndmask_b32_e64 v169, 0, v201, s[80:81]
	v_cndmask_b32_e64 v170, 0, v202, s[80:81]
	v_cndmask_b32_e64 v171, 0, v203, s[80:81]
	s_waitcnt vmcnt(12)
	v_cndmask_b32_e64 v172, 0, v204, s[82:83]
	v_cndmask_b32_e64 v173, 0, v205, s[82:83]
	v_cndmask_b32_e64 v174, 0, v206, s[82:83]
	v_cndmask_b32_e64 v175, 0, v207, s[82:83]
	s_waitcnt vmcnt(11)
	v_cndmask_b32_e64 v176, 0, v208, s[84:85]
	v_cndmask_b32_e64 v177, 0, v209, s[84:85]
	v_cndmask_b32_e64 v178, 0, v210, s[84:85]
	v_cndmask_b32_e64 v179, 0, v211, s[84:85]
	s_waitcnt vmcnt(10)
; #define LAS __attribute__((address_space(3)))
; __device__ __forceinline__ float bf_lo(unsigned u) { return __uint_as_float(u << 16); }
; __device__ __forceinline__ float bf_hi(unsigned u) { return __uint_as_float(u & 0xffff0000u); }
; __device__ void conv_phase(LAS unsigned char* lds, const Params& p) {
;     ...
;             for (int hb = 0; hb < 4; ++hb) {
;                 u32x4 raw[8];
; #pragma unroll
;                 for (int q = 0; q < 8; ++q) {
;                     const int xx = base - 15 + hb * 8 + q;
;                     const int xc = min(max(xx, 0), 63);
;                     const u32x4 r = *(const u32x4*)(Pb + (offb + (unsigned)xc * stepB));
;                     const bool ok = (xx == xc);
;                     raw[q] = (u32x4){ok ? r[0] : 0u, ok ? r[1] : 0u, ok ? r[2] : 0u, ok ? r[3] : 0u};
;                 }
;                 const LAS float* wrow = wl + hb * 8 * 512 + ch0;
; #pragma unroll
;                 for (int q = 0; q < 8; ++q) {
;                     const float in[8] = {bf_lo(raw[q][0]), bf_hi(raw[q][0]), bf_lo(raw[q][1]), bf_hi(raw[q][1]), bf_lo(raw[q][2]), bf_hi(raw[q][2]), bf_lo(raw[q][3]), bf_hi(raw[q][3])};
;                     const f32x4 wa = *(const LAS f32x4*)(wrow + q * 512), wb = *(const LAS f32x4*)(wrow + q * 512 + 4);
;                     const float Wc[8] = {wa[0], wa[1], wa[2], wa[3], wb[0], wb[1], wb[2], wb[3]};
; #pragma unroll
;                     for (int c = 0; c < 8; ++c) { cur[0][c] += Wc[c] * in[c]; cur[1][c] += Wp[c] * in[c]; Wp[c] = Wc[c]; }
;                 }
	v_cndmask_b32_e64 v180, 0, v212, s[88:89]
	v_cndmask_b32_e64 v181, 0, v213, s[88:89]
	v_cndmask_b32_e64 v182, 0, v214, s[88:89]
	v_cndmask_b32_e64 v183, 0, v215, s[88:89]
	s_waitcnt vmcnt(9)
	v_cndmask_b32_e64 v184, 0, v216, s[90:91]
	v_cndmask_b32_e64 v185, 0, v217, s[90:91]
	v_cndmask_b32_e64 v186, 0, v218, s[90:91]
	v_cndmask_b32_e64 v187, 0, v219, s[90:91]
	s_waitcnt vmcnt(8)
	v_cndmask_b32_e64 v188, 0, v220, s[92:93]
	v_cndmask_b32_e64 v189, 0, v221, s[92:93]
	v_cndmask_b32_e64 v190, 0, v222, s[92:93]
	v_cndmask_b32_e64 v191, 0, v223, s[92:93]
	v_add_u32_e32 v193, 1, v115
	v_med3_i32 v194, v193, 0, 63
	v_cmp_eq_u32_e64 s[76:77], v193, v194
	v_lshl_add_u32 v192, v194, v118, v126
	v_add_u32_e32 v197, 2, v115
	v_med3_i32 v198, v197, 0, 63
	v_cmp_eq_u32_e64 s[78:79], v197, v198
	v_lshl_add_u32 v196, v198, v118, v126
	v_add_u32_e32 v201, 3, v115
	v_med3_i32 v202, v201, 0, 63
	v_cmp_eq_u32_e64 s[80:81], v201, v202
	v_lshl_add_u32 v200, v202, v118, v126
	v_add_u32_e32 v205, 4, v115
	v_med3_i32 v206, v205, 0, 63
	v_cmp_eq_u32_e64 s[82:83], v205, v206
	v_lshl_add_u32 v204, v206, v118, v126
	v_add_u32_e32 v209, 5, v115
	v_med3_i32 v210, v209, 0, 63
	v_cmp_eq_u32_e64 s[84:85], v209, v210
	v_lshl_add_u32 v208, v210, v118, v126
	v_add_u32_e32 v213, 6, v115
	v_med3_i32 v214, v213, 0, 63
	v_cmp_eq_u32_e64 s[88:89], v213, v214
	v_lshl_add_u32 v212, v214, v118, v126
	v_add_u32_e32 v217, 7, v115
	v_med3_i32 v218, v217, 0, 63
	v_cmp_eq_u32_e64 s[90:91], v217, v218
	v_lshl_add_u32 v216, v218, v118, v126
	v_add_u32_e32 v221, 8, v115
	v_med3_i32 v222, v221, 0, 63
	v_cmp_eq_u32_e64 s[92:93], v221, v222
	v_lshl_add_u32 v220, v222, v118, v126
	global_load_dwordx4 v[192:195], v192, s[26:27]
	s_nop 0
	global_load_dwordx4 v[196:199], v196, s[26:27]
	s_nop 0
	global_load_dwordx4 v[200:203], v200, s[26:27]
	s_nop 0
	global_load_dwordx4 v[204:207], v204, s[26:27]
	s_nop 0
	global_load_dwordx4 v[208:211], v208, s[26:27]
	s_nop 0
	global_load_dwordx4 v[212:215], v212, s[26:27]
	s_nop 0
	global_load_dwordx4 v[216:219], v216, s[26:27]
	s_nop 0
	global_load_dwordx4 v[220:223], v220, s[26:27]
	v_lshlrev_b32_e32 v128, 16, v160
	v_and_b32_e32 v129, 0xffff0000, v160
	v_lshlrev_b32_e32 v130, 16, v161
	v_and_b32_e32 v131, 0xffff0000, v161
	v_lshlrev_b32_e32 v132, 16, v162
	v_and_b32_e32 v133, 0xffff0000, v162
	v_lshlrev_b32_e32 v134, 16, v163
	v_and_b32_e32 v135, 0xffff0000, v163
	v_lshlrev_b32_e32 v136, 16, v164
	v_and_b32_e32 v137, 0xffff0000, v164
	v_lshlrev_b32_e32 v138, 16, v165
	v_and_b32_e32 v139, 0xffff0000, v165
	v_lshlrev_b32_e32 v140, 16, v166
	v_and_b32_e32 v141, 0xffff0000, v166
	v_lshlrev_b32_e32 v142, 16, v167
	v_and_b32_e32 v143, 0xffff0000, v167
	v_pk_fma_f32 v[104:105], v[6:7], v[128:129], v[104:105]
	v_pk_fma_f32 v[102:103], v[8:9], v[130:131], v[102:103]
	v_pk_fma_f32 v[100:101], v[2:3], v[132:133], v[100:101]
	v_pk_fma_f32 v[116:117], v[4:5], v[134:135], v[116:117]
	s_waitcnt lgkmcnt(12)
	v_pk_fma_f32 v[112:113], v[12:13], v[134:135], v[112:113]
	v_pk_fma_f32 v[110:111], v[14:15], v[128:129], v[110:111]
	v_pk_fma_f32 v[108:109], v[16:17], v[130:131], v[108:109]
	v_pk_fma_f32 v[106:107], v[10:11], v[132:133], v[106:107]
	v_lshlrev_b32_e32 v144, 16, v168
	v_and_b32_e32 v145, 0xffff0000, v168
	v_lshlrev_b32_e32 v146, 16, v169
	v_and_b32_e32 v147, 0xffff0000, v169
	v_lshlrev_b32_e32 v148, 16, v170
	v_and_b32_e32 v149, 0xffff0000, v170
	v_lshlrev_b32_e32 v150, 16, v171
	v_and_b32_e32 v151, 0xffff0000, v171
	v_pk_fma_f32 v[12:13], v[12:13], v[142:143], v[116:117]
	s_waitcnt lgkmcnt(10)
	v_pk_fma_f32 v[112:113], v[20:21], v[142:143], v[112:113]
	v_pk_fma_f32 v[110:111], v[22:23], v[136:137], v[110:111]
	v_pk_fma_f32 v[14:15], v[14:15], v[136:137], v[104:105]
	v_pk_fma_f32 v[104:105], v[24:25], v[138:139], v[108:109]
	v_pk_fma_f32 v[16:17], v[16:17], v[138:139], v[102:103]
	v_pk_fma_f32 v[102:103], v[18:19], v[140:141], v[106:107]
	v_pk_fma_f32 v[10:11], v[10:11], v[140:141], v[100:101]
	v_lshlrev_b32_e32 v152, 16, v172
	v_and_b32_e32 v153, 0xffff0000, v172
	v_lshlrev_b32_e32 v154, 16, v173
	v_and_b32_e32 v155, 0xffff0000, v173
	v_lshlrev_b32_e32 v156, 16, v174
	v_and_b32_e32 v157, 0xffff0000, v174
	v_lshlrev_b32_e32 v158, 16, v175
	v_and_b32_e32 v159, 0xffff0000, v175
	ds_read_b128 v[6:9], v127 offset:14336
	ds_read_b128 v[2:5], v127 offset:14352
	v_pk_fma_f32 v[12:13], v[20:21], v[150:151], v[12:13]
	s_waitcnt lgkmcnt(10)
	v_pk_fma_f32 v[20:21], v[28:29], v[150:151], v[112:113]
	v_pk_fma_f32 v[100:101], v[30:31], v[144:145], v[110:111]
	v_pk_fma_f32 v[14:15], v[22:23], v[144:145], v[14:15]
	v_pk_fma_f32 v[22:23], v[32:33], v[146:147], v[104:105]
	v_pk_fma_f32 v[16:17], v[24:25], v[146:147], v[16:17]
	v_pk_fma_f32 v[24:25], v[26:27], v[148:149], v[102:103]
	v_pk_fma_f32 v[10:11], v[18:19], v[148:149], v[10:11]
	v_lshlrev_b32_e32 v160, 16, v176
	v_and_b32_e32 v161, 0xffff0000, v176
	v_lshlrev_b32_e32 v162, 16, v177
	v_and_b32_e32 v163, 0xffff0000, v177
	v_lshlrev_b32_e32 v164, 16, v178
	v_and_b32_e32 v165, 0xffff0000, v178
	v_lshlrev_b32_e32 v166, 16, v179
	v_and_b32_e32 v167, 0xffff0000, v179
	v_pk_fma_f32 v[12:13], v[28:29], v[158:159], v[12:13]
	s_waitcnt lgkmcnt(8)
	v_pk_fma_f32 v[18:19], v[36:37], v[158:159], v[20:21]
	v_pk_fma_f32 v[20:21], v[38:39], v[152:153], v[100:101]
	v_pk_fma_f32 v[14:15], v[30:31], v[152:153], v[14:15]
	v_pk_fma_f32 v[22:23], v[40:41], v[154:155], v[22:23]
	v_pk_fma_f32 v[16:17], v[32:33], v[154:155], v[16:17]
	v_pk_fma_f32 v[24:25], v[34:35], v[156:157], v[24:25]
	v_pk_fma_f32 v[10:11], v[26:27], v[156:157], v[10:11]
	v_lshlrev_b32_e32 v168, 16, v180
	v_and_b32_e32 v169, 0xffff0000, v180
	v_lshlrev_b32_e32 v170, 16, v181
	v_and_b32_e32 v171, 0xffff0000, v181
	v_lshlrev_b32_e32 v172, 16, v182
	v_and_b32_e32 v173, 0xffff0000, v182
	v_lshlrev_b32_e32 v174, 16, v183
	v_and_b32_e32 v175, 0xffff0000, v183
	v_pk_fma_f32 v[12:13], v[36:37], v[166:167], v[12:13]
	s_waitcnt lgkmcnt(6)
; #define LAS __attribute__((address_space(3)))
; __device__ __forceinline__ float bf_lo(unsigned u) { return __uint_as_float(u << 16); }
; __device__ __forceinline__ float bf_hi(unsigned u) { return __uint_as_float(u & 0xffff0000u); }
; __device__ void conv_phase(LAS unsigned char* lds, const Params& p) {
;     ...
;                 const LAS float* wrow = wl + hb * 8 * 512 + ch0;
; #pragma unroll
;                 for (int q = 0; q < 8; ++q) {
;                     const float in[8] = {bf_lo(raw[q][0]), bf_hi(raw[q][0]), bf_lo(raw[q][1]), bf_hi(raw[q][1]), bf_lo(raw[q][2]), bf_hi(raw[q][2]), bf_lo(raw[q][3]), bf_hi(raw[q][3])};
;                     const f32x4 wa = *(const LAS f32x4*)(wrow + q * 512), wb = *(const LAS f32x4*)(wrow + q * 512 + 4);
;                     const float Wc[8] = {wa[0], wa[1], wa[2], wa[3], wb[0], wb[1], wb[2], wb[3]};
; #pragma unroll
;                     for (int c = 0; c < 8; ++c) { cur[0][c] += Wc[c] * in[c]; cur[1][c] += Wp[c] * in[c]; Wp[c] = Wc[c]; }
;                 }
	v_pk_fma_f32 v[18:19], v[44:45], v[166:167], v[18:19]
	v_pk_fma_f32 v[20:21], v[46:47], v[160:161], v[20:21]
	v_pk_fma_f32 v[14:15], v[38:39], v[160:161], v[14:15]
	v_pk_fma_f32 v[22:23], v[48:49], v[162:163], v[22:23]
	v_pk_fma_f32 v[16:17], v[40:41], v[162:163], v[16:17]
	v_pk_fma_f32 v[24:25], v[42:43], v[164:165], v[24:25]
	v_pk_fma_f32 v[10:11], v[34:35], v[164:165], v[10:11]
	v_lshlrev_b32_e32 v176, 16, v184
	v_and_b32_e32 v177, 0xffff0000, v184
	v_lshlrev_b32_e32 v178, 16, v185
	v_and_b32_e32 v179, 0xffff0000, v185
	v_lshlrev_b32_e32 v180, 16, v186
	v_and_b32_e32 v181, 0xffff0000, v186
	v_lshlrev_b32_e32 v183, 16, v187
	v_and_b32_e32 v182, 0xffff0000, v187
	v_lshlrev_b32_e32 v184, 16, v188
	v_and_b32_e32 v185, 0xffff0000, v188
	v_lshlrev_b32_e32 v186, 16, v189
	v_and_b32_e32 v187, 0xffff0000, v189
	v_lshlrev_b32_e32 v188, 16, v190
	v_and_b32_e32 v189, 0xffff0000, v190
	v_lshlrev_b32_e32 v190, 16, v191
	v_and_b32_e32 v191, 0xffff0000, v191
	v_pk_fma_f32 v[12:13], v[44:45], v[174:175], v[12:13]
	s_waitcnt lgkmcnt(4)
	v_pk_fma_f32 v[18:19], v[52:53], v[174:175], v[18:19]
	v_pk_fma_f32 v[20:21], v[54:55], v[168:169], v[20:21]
	v_pk_fma_f32 v[14:15], v[46:47], v[168:169], v[14:15]
	v_pk_fma_f32 v[22:23], v[56:57], v[170:171], v[22:23]
	v_pk_fma_f32 v[16:17], v[48:49], v[170:171], v[16:17]
	v_pk_fma_f32 v[24:25], v[50:51], v[172:173], v[24:25]
	v_pk_fma_f32 v[10:11], v[42:43], v[172:173], v[10:11]
	s_waitcnt lgkmcnt(2)
	v_pk_mul_f32 v[128:129], v[60:61], v[190:191]
	v_pk_fma_f32 v[18:19], v[60:61], v[182:183], v[18:19] op_sel:[0,1,0] op_sel_hi:[1,0,1]
	v_pk_fma_f32 v[20:21], v[62:63], v[176:177], v[20:21]
	v_pk_fma_f32 v[14:15], v[54:55], v[176:177], v[14:15]
	v_pk_fma_f32 v[22:23], v[64:65], v[178:179], v[22:23]
	v_pk_fma_f32 v[16:17], v[56:57], v[178:179], v[16:17]
	v_pk_fma_f32 v[24:25], v[58:59], v[180:181], v[24:25]
	v_pk_fma_f32 v[10:11], v[50:51], v[180:181], v[10:11]
	v_pk_fma_f32 v[12:13], v[52:53], v[182:183], v[12:13] op_sel:[1,0,1] op_sel_hi:[0,1,0]
	v_add_u32_e32 v127, 0x4000, v127
	s_waitcnt lgkmcnt(1)
	v_pk_fma_f32 v[110:111], v[6:7], v[184:185], v[20:21]
	v_pk_fma_f32 v[104:105], v[62:63], v[184:185], v[14:15]
	v_pk_fma_f32 v[108:109], v[8:9], v[186:187], v[22:23]
	v_pk_fma_f32 v[102:103], v[64:65], v[186:187], v[16:17]
	s_waitcnt lgkmcnt(0)
	v_pk_fma_f32 v[106:107], v[2:3], v[188:189], v[24:25]
	v_pk_fma_f32 v[100:101], v[58:59], v[188:189], v[10:11]
	v_pk_fma_f32 v[112:113], v[4:5], v[190:191], v[18:19]
	v_pk_add_f32 v[34:35], v[12:13], v[128:129] op_sel:[0,1] op_sel_hi:[1,0]
	ds_read_b128 v[14:17], v127
	ds_read_b128 v[10:13], v127 offset:16
	v_mov_b32_e32 v116, v35
	v_mov_b32_e32 v117, v34
	ds_read_b128 v[22:25], v127 offset:2048
	ds_read_b128 v[18:21], v127 offset:2064
	ds_read_b128 v[30:33], v127 offset:4096
	ds_read_b128 v[26:29], v127 offset:4112
	ds_read_b128 v[38:41], v127 offset:6144
	ds_read_b128 v[34:37], v127 offset:6160
	ds_read_b128 v[46:49], v127 offset:8192
	ds_read_b128 v[42:45], v127 offset:8208
	ds_read_b128 v[54:57], v127 offset:10240
	ds_read_b128 v[50:53], v127 offset:10256
	ds_read_b128 v[62:65], v127 offset:12288
	ds_read_b128 v[58:61], v127 offset:12304
	s_waitcnt vmcnt(15)
	v_cndmask_b32_e64 v160, 0, v224, s[42:43]
	v_cndmask_b32_e64 v161, 0, v225, s[42:43]
	v_cndmask_b32_e64 v162, 0, v226, s[42:43]
	v_cndmask_b32_e64 v163, 0, v227, s[42:43]
	s_waitcnt vmcnt(14)
	v_cndmask_b32_e64 v164, 0, v228, s[44:45]
	v_cndmask_b32_e64 v165, 0, v229, s[44:45]
	v_cndmask_b32_e64 v166, 0, v230, s[44:45]
	v_cndmask_b32_e64 v167, 0, v231, s[44:45]
	s_waitcnt vmcnt(13)
	v_cndmask_b32_e64 v168, 0, v232, s[46:47]
	v_cndmask_b32_e64 v169, 0, v233, s[46:47]
	v_cndmask_b32_e64 v170, 0, v234, s[46:47]
	v_cndmask_b32_e64 v171, 0, v235, s[46:47]
	s_waitcnt vmcnt(12)
	v_cndmask_b32_e64 v172, 0, v236, s[50:51]
	v_cndmask_b32_e64 v173, 0, v237, s[50:51]
	v_cndmask_b32_e64 v174, 0, v238, s[50:51]
	v_cndmask_b32_e64 v175, 0, v239, s[50:51]
	s_waitcnt vmcnt(11)
	v_cndmask_b32_e64 v176, 0, v240, s[52:53]
	v_cndmask_b32_e64 v177, 0, v241, s[52:53]
	v_cndmask_b32_e64 v178, 0, v242, s[52:53]
	v_cndmask_b32_e64 v179, 0, v243, s[52:53]
	s_waitcnt vmcnt(10)
	v_cndmask_b32_e64 v180, 0, v244, s[64:65]
	v_cndmask_b32_e64 v181, 0, v245, s[64:65]
	v_cndmask_b32_e64 v182, 0, v246, s[64:65]
	v_cndmask_b32_e64 v183, 0, v247, s[64:65]
	s_waitcnt vmcnt(9)
	v_cndmask_b32_e64 v184, 0, v248, s[94:95]
	v_cndmask_b32_e64 v185, 0, v249, s[94:95]
	v_cndmask_b32_e64 v186, 0, v250, s[94:95]
	v_cndmask_b32_e64 v187, 0, v251, s[94:95]
	s_waitcnt vmcnt(8)
; #define LAS __attribute__((address_space(3)))
; __device__ __forceinline__ float bf_lo(unsigned u) { return __uint_as_float(u << 16); }
; __device__ __forceinline__ float bf_hi(unsigned u) { return __uint_as_float(u & 0xffff0000u); }
; __device__ void conv_phase(LAS unsigned char* lds, const Params& p) {
;     ...
;                 for (int q = 0; q < 8; ++q) {
;                     const int xx = base - 15 + hb * 8 + q;
;                     const int xc = min(max(xx, 0), 63);
;                     const u32x4 r = *(const u32x4*)(Pb + (offb + (unsigned)xc * stepB));
;                     const bool ok = (xx == xc);
;                     raw[q] = (u32x4){ok ? r[0] : 0u, ok ? r[1] : 0u, ok ? r[2] : 0u, ok ? r[3] : 0u};
;                 }
;                 const LAS float* wrow = wl + hb * 8 * 512 + ch0;
; #pragma unroll
;                 for (int q = 0; q < 8; ++q) {
;                     const float in[8] = {bf_lo(raw[q][0]), bf_hi(raw[q][0]), bf_lo(raw[q][1]), bf_hi(raw[q][1]), bf_lo(raw[q][2]), bf_hi(raw[q][2]), bf_lo(raw[q][3]), bf_hi(raw[q][3])};
;                     const f32x4 wa = *(const LAS f32x4*)(wrow + q * 512), wb = *(const LAS f32x4*)(wrow + q * 512 + 4);
;                     const float Wc[8] = {wa[0], wa[1], wa[2], wa[3], wb[0], wb[1], wb[2], wb[3]};
; #pragma unroll
;                     for (int c = 0; c < 8; ++c) { cur[0][c] += Wc[c] * in[c]; cur[1][c] += Wp[c] * in[c]; Wp[c] = Wc[c]; }
;                 }
	v_cndmask_b32_e64 v188, 0, v252, s[96:97]
	v_cndmask_b32_e64 v189, 0, v253, s[96:97]
	v_cndmask_b32_e64 v190, 0, v254, s[96:97]
	v_cndmask_b32_e64 v191, 0, v255, s[96:97]
	v_add_u32_e32 v225, 9, v115
	v_med3_i32 v226, v225, 0, 63
	v_cmp_eq_u32_e64 s[42:43], v225, v226
	v_lshl_add_u32 v224, v226, v118, v126
	v_add_u32_e32 v229, 10, v115
	v_med3_i32 v230, v229, 0, 63
	v_cmp_eq_u32_e64 s[44:45], v229, v230
	v_lshl_add_u32 v228, v230, v118, v126
	v_add_u32_e32 v233, 11, v115
	v_med3_i32 v234, v233, 0, 63
	v_cmp_eq_u32_e64 s[46:47], v233, v234
	v_lshl_add_u32 v232, v234, v118, v126
	v_add_u32_e32 v237, 12, v115
	v_med3_i32 v238, v237, 0, 63
	v_cmp_eq_u32_e64 s[50:51], v237, v238
	v_lshl_add_u32 v236, v238, v118, v126
	v_add_u32_e32 v241, 13, v115
	v_med3_i32 v242, v241, 0, 63
	v_cmp_eq_u32_e64 s[52:53], v241, v242
	v_lshl_add_u32 v240, v242, v118, v126
	v_add_u32_e32 v245, 14, v115
	v_med3_i32 v246, v245, 0, 63
	v_cmp_eq_u32_e64 s[64:65], v245, v246
	v_lshl_add_u32 v244, v246, v118, v126
	v_add_u32_e32 v249, 15, v115
	v_med3_i32 v250, v249, 0, 63
	v_cmp_eq_u32_e64 s[94:95], v249, v250
	v_lshl_add_u32 v248, v250, v118, v126
	v_add_u32_e32 v253, 16, v115
	v_med3_i32 v254, v253, 0, 63
	v_cmp_eq_u32_e64 s[96:97], v253, v254
	v_lshl_add_u32 v252, v254, v118, v126
	global_load_dwordx4 v[224:227], v224, s[26:27]
	s_nop 0
	global_load_dwordx4 v[228:231], v228, s[26:27]
	s_nop 0
	global_load_dwordx4 v[232:235], v232, s[26:27]
	s_nop 0
	global_load_dwordx4 v[236:239], v236, s[26:27]
	s_nop 0
	global_load_dwordx4 v[240:243], v240, s[26:27]
	s_nop 0
	global_load_dwordx4 v[244:247], v244, s[26:27]
	s_nop 0
	global_load_dwordx4 v[248:251], v248, s[26:27]
	s_nop 0
	global_load_dwordx4 v[252:255], v252, s[26:27]
	v_lshlrev_b32_e32 v128, 16, v160
	v_and_b32_e32 v129, 0xffff0000, v160
	v_lshlrev_b32_e32 v130, 16, v161
	v_and_b32_e32 v131, 0xffff0000, v161
	v_lshlrev_b32_e32 v132, 16, v162
	v_and_b32_e32 v133, 0xffff0000, v162
	v_lshlrev_b32_e32 v134, 16, v163
	v_and_b32_e32 v135, 0xffff0000, v163
	v_lshlrev_b32_e32 v136, 16, v164
	v_and_b32_e32 v137, 0xffff0000, v164
	v_lshlrev_b32_e32 v138, 16, v165
	v_and_b32_e32 v139, 0xffff0000, v165
	v_lshlrev_b32_e32 v140, 16, v166
	v_and_b32_e32 v141, 0xffff0000, v166
	v_lshlrev_b32_e32 v142, 16, v167
	v_and_b32_e32 v143, 0xffff0000, v167
	v_pk_fma_f32 v[104:105], v[6:7], v[128:129], v[104:105]
	v_pk_fma_f32 v[102:103], v[8:9], v[130:131], v[102:103]
	v_pk_fma_f32 v[100:101], v[2:3], v[132:133], v[100:101]
	v_pk_fma_f32 v[116:117], v[4:5], v[134:135], v[116:117]
	s_waitcnt lgkmcnt(12)
	v_pk_fma_f32 v[112:113], v[12:13], v[134:135], v[112:113]
	v_pk_fma_f32 v[110:111], v[14:15], v[128:129], v[110:111]
	v_pk_fma_f32 v[108:109], v[16:17], v[130:131], v[108:109]
	v_pk_fma_f32 v[106:107], v[10:11], v[132:133], v[106:107]
	v_lshlrev_b32_e32 v144, 16, v168
	v_and_b32_e32 v145, 0xffff0000, v168
	v_lshlrev_b32_e32 v146, 16, v169
	v_and_b32_e32 v147, 0xffff0000, v169
	v_lshlrev_b32_e32 v148, 16, v170
	v_and_b32_e32 v149, 0xffff0000, v170
	v_lshlrev_b32_e32 v150, 16, v171
	v_and_b32_e32 v151, 0xffff0000, v171
	v_pk_fma_f32 v[12:13], v[12:13], v[142:143], v[116:117]
	s_waitcnt lgkmcnt(10)
	v_pk_fma_f32 v[112:113], v[20:21], v[142:143], v[112:113]
	v_pk_fma_f32 v[110:111], v[22:23], v[136:137], v[110:111]
	v_pk_fma_f32 v[14:15], v[14:15], v[136:137], v[104:105]
	v_pk_fma_f32 v[104:105], v[24:25], v[138:139], v[108:109]
	v_pk_fma_f32 v[16:17], v[16:17], v[138:139], v[102:103]
	v_pk_fma_f32 v[102:103], v[18:19], v[140:141], v[106:107]
	v_pk_fma_f32 v[10:11], v[10:11], v[140:141], v[100:101]
	v_lshlrev_b32_e32 v152, 16, v172
	v_and_b32_e32 v153, 0xffff0000, v172
	v_lshlrev_b32_e32 v154, 16, v173
	v_and_b32_e32 v155, 0xffff0000, v173
	v_lshlrev_b32_e32 v156, 16, v174
	v_and_b32_e32 v157, 0xffff0000, v174
	v_lshlrev_b32_e32 v158, 16, v175
	v_and_b32_e32 v159, 0xffff0000, v175
	ds_read_b128 v[6:9], v127 offset:14336
	ds_read_b128 v[2:5], v127 offset:14352
	v_pk_fma_f32 v[12:13], v[20:21], v[150:151], v[12:13]
	s_waitcnt lgkmcnt(10)
	v_pk_fma_f32 v[20:21], v[28:29], v[150:151], v[112:113]
	v_pk_fma_f32 v[100:101], v[30:31], v[144:145], v[110:111]
	v_pk_fma_f32 v[14:15], v[22:23], v[144:145], v[14:15]
	v_pk_fma_f32 v[22:23], v[32:33], v[146:147], v[104:105]
	v_pk_fma_f32 v[16:17], v[24:25], v[146:147], v[16:17]
	v_pk_fma_f32 v[24:25], v[26:27], v[148:149], v[102:103]
	v_pk_fma_f32 v[10:11], v[18:19], v[148:149], v[10:11]
	v_lshlrev_b32_e32 v160, 16, v176
	v_and_b32_e32 v161, 0xffff0000, v176
	v_lshlrev_b32_e32 v162, 16, v177
	v_and_b32_e32 v163, 0xffff0000, v177
	v_lshlrev_b32_e32 v164, 16, v178
	v_and_b32_e32 v165, 0xffff0000, v178
	v_lshlrev_b32_e32 v166, 16, v179
	v_and_b32_e32 v167, 0xffff0000, v179
	v_pk_fma_f32 v[12:13], v[28:29], v[158:159], v[12:13]
	s_waitcnt lgkmcnt(8)
	v_pk_fma_f32 v[18:19], v[36:37], v[158:159], v[20:21]
	v_pk_fma_f32 v[20:21], v[38:39], v[152:153], v[100:101]
	v_pk_fma_f32 v[14:15], v[30:31], v[152:153], v[14:15]
	v_pk_fma_f32 v[22:23], v[40:41], v[154:155], v[22:23]
	v_pk_fma_f32 v[16:17], v[32:33], v[154:155], v[16:17]
	v_pk_fma_f32 v[24:25], v[34:35], v[156:157], v[24:25]
	v_pk_fma_f32 v[10:11], v[26:27], v[156:157], v[10:11]
	v_lshlrev_b32_e32 v168, 16, v180
	v_and_b32_e32 v169, 0xffff0000, v180
	v_lshlrev_b32_e32 v170, 16, v181
	v_and_b32_e32 v171, 0xffff0000, v181
	v_lshlrev_b32_e32 v172, 16, v182
	v_and_b32_e32 v173, 0xffff0000, v182
	v_lshlrev_b32_e32 v174, 16, v183
	v_and_b32_e32 v175, 0xffff0000, v183
	v_pk_fma_f32 v[12:13], v[36:37], v[166:167], v[12:13]
	s_waitcnt lgkmcnt(6)
; #define LAS __attribute__((address_space(3)))
; __device__ __forceinline__ float bf_lo(unsigned u) { return __uint_as_float(u << 16); }
; __device__ __forceinline__ float bf_hi(unsigned u) { return __uint_as_float(u & 0xffff0000u); }
; __device__ void conv_phase(LAS unsigned char* lds, const Params& p) {
;     ...
; #pragma unroll
;                 for (int q = 0; q < 8; ++q) {
;                     const int xx = base - 15 + hb * 8 + q;
;                     const int xc = min(max(xx, 0), 63);
;                     const u32x4 r = *(const u32x4*)(Pb + (offb + (unsigned)xc * stepB));
;                     const bool ok = (xx == xc);
;                     raw[q] = (u32x4){ok ? r[0] : 0u, ok ? r[1] : 0u, ok ? r[2] : 0u, ok ? r[3] : 0u};
;                 }
;                 const LAS float* wrow = wl + hb * 8 * 512 + ch0;
; #pragma unroll
;                 for (int q = 0; q < 8; ++q) {
;                     const float in[8] = {bf_lo(raw[q][0]), bf_hi(raw[q][0]), bf_lo(raw[q][1]), bf_hi(raw[q][1]), bf_lo(raw[q][2]), bf_hi(raw[q][2]), bf_lo(raw[q][3]), bf_hi(raw[q][3])};
;                     const f32x4 wa = *(const LAS f32x4*)(wrow + q * 512), wb = *(const LAS f32x4*)(wrow + q * 512 + 4);
;                     const float Wc[8] = {wa[0], wa[1], wa[2], wa[3], wb[0], wb[1], wb[2], wb[3]};
; #pragma unroll
;                     for (int c = 0; c < 8; ++c) { cur[0][c] += Wc[c] * in[c]; cur[1][c] += Wp[c] * in[c]; Wp[c] = Wc[c]; }
;                 }
	v_pk_fma_f32 v[18:19], v[44:45], v[166:167], v[18:19]
	v_pk_fma_f32 v[20:21], v[46:47], v[160:161], v[20:21]
	v_pk_fma_f32 v[14:15], v[38:39], v[160:161], v[14:15]
	v_pk_fma_f32 v[22:23], v[48:49], v[162:163], v[22:23]
	v_pk_fma_f32 v[16:17], v[40:41], v[162:163], v[16:17]
	v_pk_fma_f32 v[24:25], v[42:43], v[164:165], v[24:25]
	v_pk_fma_f32 v[10:11], v[34:35], v[164:165], v[10:11]
	v_lshlrev_b32_e32 v176, 16, v184
	v_and_b32_e32 v177, 0xffff0000, v184
	v_lshlrev_b32_e32 v178, 16, v185
	v_and_b32_e32 v179, 0xffff0000, v185
	v_lshlrev_b32_e32 v180, 16, v186
	v_and_b32_e32 v181, 0xffff0000, v186
	v_lshlrev_b32_e32 v183, 16, v187
	v_and_b32_e32 v182, 0xffff0000, v187
	v_lshlrev_b32_e32 v184, 16, v188
	v_and_b32_e32 v185, 0xffff0000, v188
	v_lshlrev_b32_e32 v186, 16, v189
	v_and_b32_e32 v187, 0xffff0000, v189
	v_lshlrev_b32_e32 v188, 16, v190
	v_and_b32_e32 v189, 0xffff0000, v190
	v_lshlrev_b32_e32 v190, 16, v191
	v_and_b32_e32 v191, 0xffff0000, v191
	v_pk_fma_f32 v[12:13], v[44:45], v[174:175], v[12:13]
	s_waitcnt lgkmcnt(4)
	v_pk_fma_f32 v[18:19], v[52:53], v[174:175], v[18:19]
	v_pk_fma_f32 v[20:21], v[54:55], v[168:169], v[20:21]
	v_pk_fma_f32 v[14:15], v[46:47], v[168:169], v[14:15]
	v_pk_fma_f32 v[22:23], v[56:57], v[170:171], v[22:23]
	v_pk_fma_f32 v[16:17], v[48:49], v[170:171], v[16:17]
	v_pk_fma_f32 v[24:25], v[50:51], v[172:173], v[24:25]
	v_pk_fma_f32 v[10:11], v[42:43], v[172:173], v[10:11]
	s_waitcnt lgkmcnt(2)
	v_pk_mul_f32 v[128:129], v[60:61], v[190:191]
	v_pk_fma_f32 v[18:19], v[60:61], v[182:183], v[18:19] op_sel:[0,1,0] op_sel_hi:[1,0,1]
	v_pk_fma_f32 v[20:21], v[62:63], v[176:177], v[20:21]
	v_pk_fma_f32 v[14:15], v[54:55], v[176:177], v[14:15]
	v_pk_fma_f32 v[22:23], v[64:65], v[178:179], v[22:23]
	v_pk_fma_f32 v[16:17], v[56:57], v[178:179], v[16:17]
	v_pk_fma_f32 v[24:25], v[58:59], v[180:181], v[24:25]
	v_pk_fma_f32 v[10:11], v[50:51], v[180:181], v[10:11]
	v_pk_fma_f32 v[12:13], v[52:53], v[182:183], v[12:13] op_sel:[1,0,1] op_sel_hi:[0,1,0]
	v_add_u32_e32 v127, 0x4000, v127
	s_waitcnt lgkmcnt(1)
	v_pk_fma_f32 v[110:111], v[6:7], v[184:185], v[20:21]
	v_pk_fma_f32 v[104:105], v[62:63], v[184:185], v[14:15]
	v_pk_fma_f32 v[108:109], v[8:9], v[186:187], v[22:23]
	v_pk_fma_f32 v[102:103], v[64:65], v[186:187], v[16:17]
	s_waitcnt lgkmcnt(0)
	v_pk_fma_f32 v[106:107], v[2:3], v[188:189], v[24:25]
	v_pk_fma_f32 v[100:101], v[58:59], v[188:189], v[10:11]
	v_pk_fma_f32 v[112:113], v[4:5], v[190:191], v[18:19]
	v_pk_add_f32 v[34:35], v[12:13], v[128:129] op_sel:[0,1] op_sel_hi:[1,0]
	ds_read_b128 v[14:17], v127
	ds_read_b128 v[10:13], v127 offset:16
	v_mov_b32_e32 v116, v35
	v_mov_b32_e32 v117, v34
	ds_read_b128 v[22:25], v127 offset:2048
	ds_read_b128 v[18:21], v127 offset:2064
	ds_read_b128 v[30:33], v127 offset:4096
	ds_read_b128 v[26:29], v127 offset:4112
	ds_read_b128 v[38:41], v127 offset:6144
	ds_read_b128 v[34:37], v127 offset:6160
	ds_read_b128 v[46:49], v127 offset:8192
	ds_read_b128 v[42:45], v127 offset:8208
	ds_read_b128 v[54:57], v127 offset:10240
	ds_read_b128 v[50:53], v127 offset:10256
	ds_read_b128 v[62:65], v127 offset:12288
	ds_read_b128 v[58:61], v127 offset:12304
	s_waitcnt vmcnt(15)
	v_cndmask_b32_e64 v160, 0, v192, s[76:77]
	v_cndmask_b32_e64 v161, 0, v193, s[76:77]
	v_cndmask_b32_e64 v162, 0, v194, s[76:77]
	v_cndmask_b32_e64 v163, 0, v195, s[76:77]
	s_waitcnt vmcnt(14)
	v_cndmask_b32_e64 v164, 0, v196, s[78:79]
	v_cndmask_b32_e64 v165, 0, v197, s[78:79]
	v_cndmask_b32_e64 v166, 0, v198, s[78:79]
	v_cndmask_b32_e64 v167, 0, v199, s[78:79]
	s_waitcnt vmcnt(13)
	v_cndmask_b32_e64 v168, 0, v200, s[80:81]
	v_cndmask_b32_e64 v169, 0, v201, s[80:81]
	v_cndmask_b32_e64 v170, 0, v202, s[80:81]
	v_cndmask_b32_e64 v171, 0, v203, s[80:81]
	s_waitcnt vmcnt(12)
	v_cndmask_b32_e64 v172, 0, v204, s[82:83]
	v_cndmask_b32_e64 v173, 0, v205, s[82:83]
	v_cndmask_b32_e64 v174, 0, v206, s[82:83]
	v_cndmask_b32_e64 v175, 0, v207, s[82:83]
	s_waitcnt vmcnt(11)
	v_cndmask_b32_e64 v176, 0, v208, s[84:85]
	v_cndmask_b32_e64 v177, 0, v209, s[84:85]
	v_cndmask_b32_e64 v178, 0, v210, s[84:85]
	v_cndmask_b32_e64 v179, 0, v211, s[84:85]
	s_waitcnt vmcnt(10)
	v_cndmask_b32_e64 v180, 0, v212, s[88:89]
	v_cndmask_b32_e64 v181, 0, v213, s[88:89]
	v_cndmask_b32_e64 v182, 0, v214, s[88:89]
	v_cndmask_b32_e64 v183, 0, v215, s[88:89]
	s_waitcnt vmcnt(9)
	v_cndmask_b32_e64 v184, 0, v216, s[90:91]
	v_cndmask_b32_e64 v185, 0, v217, s[90:91]
	v_cndmask_b32_e64 v186, 0, v218, s[90:91]
	v_cndmask_b32_e64 v187, 0, v219, s[90:91]
	s_waitcnt vmcnt(8)
	v_cndmask_b32_e64 v188, 0, v220, s[92:93]
	v_cndmask_b32_e64 v189, 0, v221, s[92:93]
	v_cndmask_b32_e64 v190, 0, v222, s[92:93]
	v_cndmask_b32_e64 v191, 0, v223, s[92:93]
	s_cmp_lg_u32 s10, 0
	s_cbranch_scc1 .Lp4_nopf_2
	v_or_b32_e32 v193, 1, v124
	v_lshlrev_b32_e32 v193, 6, v193
	v_or_b32_e32 v194, 1, v123
	v_cndmask_b32_e64 v194, v194, v193, s[6:7]
	v_lshl_or_b32 v195, v194, 10, v125
	v_add_u32_e32 v193, -15, v115
	v_med3_i32 v194, v193, 0, 63
	v_cmp_eq_u32_e64 s[76:77], v193, v194
	v_lshl_add_u32 v192, v194, v118, v195
	v_add_u32_e32 v197, -14, v115
	v_med3_i32 v198, v197, 0, 63
	v_cmp_eq_u32_e64 s[78:79], v197, v198
	v_lshl_add_u32 v196, v198, v118, v195
	v_add_u32_e32 v201, -13, v115
	v_med3_i32 v202, v201, 0, 63
	v_cmp_eq_u32_e64 s[80:81], v201, v202
	v_lshl_add_u32 v200, v202, v118, v195
	v_add_u32_e32 v205, -12, v115
	v_med3_i32 v206, v205, 0, 63
	v_cmp_eq_u32_e64 s[82:83], v205, v206
	v_lshl_add_u32 v204, v206, v118, v195
	v_add_u32_e32 v209, -11, v115
	v_med3_i32 v210, v209, 0, 63
	v_cmp_eq_u32_e64 s[84:85], v209, v210
	v_lshl_add_u32 v208, v210, v118, v195
	v_add_u32_e32 v213, -10, v115
	v_med3_i32 v214, v213, 0, 63
	v_cmp_eq_u32_e64 s[88:89], v213, v214
	v_lshl_add_u32 v212, v214, v118, v195
	v_add_u32_e32 v217, -9, v115
	v_med3_i32 v218, v217, 0, 63
	v_cmp_eq_u32_e64 s[90:91], v217, v218
	v_lshl_add_u32 v216, v218, v118, v195
	v_add_u32_e32 v221, -8, v115
	v_med3_i32 v222, v221, 0, 63
	v_cmp_eq_u32_e64 s[92:93], v221, v222
	v_lshl_add_u32 v220, v222, v118, v195
	global_load_dwordx4 v[192:195], v192, s[26:27]
	s_nop 0
	global_load_dwordx4 v[196:199], v196, s[26:27]
	s_nop 0
	global_load_dwordx4 v[200:203], v200, s[26:27]
	s_nop 0
	global_load_dwordx4 v[204:207], v204, s[26:27]
	s_nop 0
	global_load_dwordx4 v[208:211], v208, s[26:27]
	s_nop 0
	global_load_dwordx4 v[212:215], v212, s[26:27]
	s_nop 0
	global_load_dwordx4 v[216:219], v216, s[26:27]
	s_nop 0
	global_load_dwordx4 v[220:223], v220, s[26:27]
; #define LAS __attribute__((address_space(3)))
; __device__ __forceinline__ float bf_lo(unsigned u) { return __uint_as_float(u << 16); }
; __device__ __forceinline__ float bf_hi(unsigned u) { return __uint_as_float(u & 0xffff0000u); }
; __device__ void conv_phase(LAS unsigned char* lds, const Params& p) {
;     ...
;                 const LAS float* wrow = wl + hb * 8 * 512 + ch0;
; #pragma unroll
;                 for (int q = 0; q < 8; ++q) {
;                     const float in[8] = {bf_lo(raw[q][0]), bf_hi(raw[q][0]), bf_lo(raw[q][1]), bf_hi(raw[q][1]), bf_lo(raw[q][2]), bf_hi(raw[q][2]), bf_lo(raw[q][3]), bf_hi(raw[q][3])};
;                     const f32x4 wa = *(const LAS f32x4*)(wrow + q * 512), wb = *(const LAS f32x4*)(wrow + q * 512 + 4);
;                     const float Wc[8] = {wa[0], wa[1], wa[2], wa[3], wb[0], wb[1], wb[2], wb[3]};
; #pragma unroll
;                     for (int c = 0; c < 8; ++c) { cur[0][c] += Wc[c] * in[c]; cur[1][c] += Wp[c] * in[c]; Wp[c] = Wc[c]; }
;                 }
.Lp4_nopf_2:
	v_lshlrev_b32_e32 v128, 16, v160
	v_and_b32_e32 v129, 0xffff0000, v160
	v_lshlrev_b32_e32 v130, 16, v161
	v_and_b32_e32 v131, 0xffff0000, v161
	v_lshlrev_b32_e32 v132, 16, v162
	v_and_b32_e32 v133, 0xffff0000, v162
	v_lshlrev_b32_e32 v134, 16, v163
	v_and_b32_e32 v135, 0xffff0000, v163
	v_lshlrev_b32_e32 v136, 16, v164
	v_and_b32_e32 v137, 0xffff0000, v164
	v_lshlrev_b32_e32 v138, 16, v165
	v_and_b32_e32 v139, 0xffff0000, v165
	v_lshlrev_b32_e32 v140, 16, v166
	v_and_b32_e32 v141, 0xffff0000, v166
	v_lshlrev_b32_e32 v142, 16, v167
	v_and_b32_e32 v143, 0xffff0000, v167
	v_pk_fma_f32 v[104:105], v[6:7], v[128:129], v[104:105]
	v_pk_fma_f32 v[102:103], v[8:9], v[130:131], v[102:103]
	v_pk_fma_f32 v[100:101], v[2:3], v[132:133], v[100:101]
	v_pk_fma_f32 v[116:117], v[4:5], v[134:135], v[116:117]
	s_waitcnt lgkmcnt(12)
	v_pk_fma_f32 v[112:113], v[12:13], v[134:135], v[112:113]
	v_pk_fma_f32 v[110:111], v[14:15], v[128:129], v[110:111]
	v_pk_fma_f32 v[108:109], v[16:17], v[130:131], v[108:109]
	v_pk_fma_f32 v[106:107], v[10:11], v[132:133], v[106:107]
	v_lshlrev_b32_e32 v144, 16, v168
	v_and_b32_e32 v145, 0xffff0000, v168
	v_lshlrev_b32_e32 v146, 16, v169
	v_and_b32_e32 v147, 0xffff0000, v169
	v_lshlrev_b32_e32 v148, 16, v170
	v_and_b32_e32 v149, 0xffff0000, v170
	v_lshlrev_b32_e32 v150, 16, v171
	v_and_b32_e32 v151, 0xffff0000, v171
	v_pk_fma_f32 v[12:13], v[12:13], v[142:143], v[116:117]
	s_waitcnt lgkmcnt(10)
	v_pk_fma_f32 v[112:113], v[20:21], v[142:143], v[112:113]
	v_pk_fma_f32 v[110:111], v[22:23], v[136:137], v[110:111]
	v_pk_fma_f32 v[14:15], v[14:15], v[136:137], v[104:105]
	v_pk_fma_f32 v[104:105], v[24:25], v[138:139], v[108:109]
	v_pk_fma_f32 v[16:17], v[16:17], v[138:139], v[102:103]
	v_pk_fma_f32 v[102:103], v[18:19], v[140:141], v[106:107]
	v_pk_fma_f32 v[10:11], v[10:11], v[140:141], v[100:101]
	v_lshlrev_b32_e32 v152, 16, v172
	v_and_b32_e32 v153, 0xffff0000, v172
	v_lshlrev_b32_e32 v154, 16, v173
	v_and_b32_e32 v155, 0xffff0000, v173
	v_lshlrev_b32_e32 v156, 16, v174
	v_and_b32_e32 v157, 0xffff0000, v174
	v_lshlrev_b32_e32 v158, 16, v175
	v_and_b32_e32 v159, 0xffff0000, v175
	ds_read_b128 v[6:9], v127 offset:14336
	ds_read_b128 v[2:5], v127 offset:14352
	v_pk_fma_f32 v[12:13], v[20:21], v[150:151], v[12:13]
	s_waitcnt lgkmcnt(10)
	v_pk_fma_f32 v[20:21], v[28:29], v[150:151], v[112:113]
	v_pk_fma_f32 v[100:101], v[30:31], v[144:145], v[110:111]
	v_pk_fma_f32 v[14:15], v[22:23], v[144:145], v[14:15]
	v_pk_fma_f32 v[22:23], v[32:33], v[146:147], v[104:105]
	v_pk_fma_f32 v[16:17], v[24:25], v[146:147], v[16:17]
	v_pk_fma_f32 v[24:25], v[26:27], v[148:149], v[102:103]
	v_pk_fma_f32 v[10:11], v[18:19], v[148:149], v[10:11]
	v_lshlrev_b32_e32 v160, 16, v176
	v_and_b32_e32 v161, 0xffff0000, v176
	v_lshlrev_b32_e32 v162, 16, v177
	v_and_b32_e32 v163, 0xffff0000, v177
	v_lshlrev_b32_e32 v164, 16, v178
	v_and_b32_e32 v165, 0xffff0000, v178
	v_lshlrev_b32_e32 v166, 16, v179
	v_and_b32_e32 v167, 0xffff0000, v179
	v_pk_fma_f32 v[12:13], v[28:29], v[158:159], v[12:13]
	s_waitcnt lgkmcnt(8)
	v_pk_fma_f32 v[18:19], v[36:37], v[158:159], v[20:21]
	v_pk_fma_f32 v[20:21], v[38:39], v[152:153], v[100:101]
	v_pk_fma_f32 v[14:15], v[30:31], v[152:153], v[14:15]
	v_pk_fma_f32 v[22:23], v[40:41], v[154:155], v[22:23]
	v_pk_fma_f32 v[16:17], v[32:33], v[154:155], v[16:17]
	v_pk_fma_f32 v[24:25], v[34:35], v[156:157], v[24:25]
	v_pk_fma_f32 v[10:11], v[26:27], v[156:157], v[10:11]
	v_lshlrev_b32_e32 v168, 16, v180
	v_and_b32_e32 v169, 0xffff0000, v180
	v_lshlrev_b32_e32 v170, 16, v181
	v_and_b32_e32 v171, 0xffff0000, v181
	v_lshlrev_b32_e32 v172, 16, v182
	v_and_b32_e32 v173, 0xffff0000, v182
	v_lshlrev_b32_e32 v174, 16, v183
	v_and_b32_e32 v175, 0xffff0000, v183
	v_pk_fma_f32 v[12:13], v[36:37], v[166:167], v[12:13]
	s_waitcnt lgkmcnt(6)
	v_pk_fma_f32 v[18:19], v[44:45], v[166:167], v[18:19]
	v_pk_fma_f32 v[20:21], v[46:47], v[160:161], v[20:21]
	v_pk_fma_f32 v[14:15], v[38:39], v[160:161], v[14:15]
	v_pk_fma_f32 v[22:23], v[48:49], v[162:163], v[22:23]
	v_pk_fma_f32 v[16:17], v[40:41], v[162:163], v[16:17]
	v_pk_fma_f32 v[24:25], v[42:43], v[164:165], v[24:25]
	v_pk_fma_f32 v[10:11], v[34:35], v[164:165], v[10:11]
	v_lshlrev_b32_e32 v176, 16, v184
	v_and_b32_e32 v177, 0xffff0000, v184
	v_lshlrev_b32_e32 v178, 16, v185
	v_and_b32_e32 v179, 0xffff0000, v185
	v_lshlrev_b32_e32 v180, 16, v186
	v_and_b32_e32 v181, 0xffff0000, v186
	v_lshlrev_b32_e32 v183, 16, v187
	v_and_b32_e32 v182, 0xffff0000, v187
	v_lshlrev_b32_e32 v184, 16, v188
	v_and_b32_e32 v185, 0xffff0000, v188
	v_lshlrev_b32_e32 v186, 16, v189
	v_and_b32_e32 v187, 0xffff0000, v189
	v_lshlrev_b32_e32 v188, 16, v190
	v_and_b32_e32 v189, 0xffff0000, v190
	v_lshlrev_b32_e32 v190, 16, v191
	v_and_b32_e32 v191, 0xffff0000, v191
	v_pk_fma_f32 v[12:13], v[44:45], v[174:175], v[12:13]
	s_waitcnt lgkmcnt(4)
	v_pk_fma_f32 v[18:19], v[52:53], v[174:175], v[18:19]
	v_pk_fma_f32 v[20:21], v[54:55], v[168:169], v[20:21]
	v_pk_fma_f32 v[14:15], v[46:47], v[168:169], v[14:15]
	v_pk_fma_f32 v[22:23], v[56:57], v[170:171], v[22:23]
	v_pk_fma_f32 v[16:17], v[48:49], v[170:171], v[16:17]
	v_pk_fma_f32 v[24:25], v[50:51], v[172:173], v[24:25]
	v_pk_fma_f32 v[10:11], v[42:43], v[172:173], v[10:11]
	s_waitcnt lgkmcnt(2)
	v_pk_mul_f32 v[128:129], v[60:61], v[190:191]
	v_pk_fma_f32 v[18:19], v[60:61], v[182:183], v[18:19] op_sel:[0,1,0] op_sel_hi:[1,0,1]
	v_pk_fma_f32 v[20:21], v[62:63], v[176:177], v[20:21]
	v_pk_fma_f32 v[14:15], v[54:55], v[176:177], v[14:15]
	v_pk_fma_f32 v[22:23], v[64:65], v[178:179], v[22:23]
	v_pk_fma_f32 v[16:17], v[56:57], v[178:179], v[16:17]
	v_pk_fma_f32 v[24:25], v[58:59], v[180:181], v[24:25]
	v_pk_fma_f32 v[10:11], v[50:51], v[180:181], v[10:11]
	v_pk_fma_f32 v[12:13], v[52:53], v[182:183], v[12:13] op_sel:[1,0,1] op_sel_hi:[0,1,0]
	v_add_u32_e32 v127, 0x4000, v127
	s_waitcnt lgkmcnt(1)
	v_pk_fma_f32 v[110:111], v[6:7], v[184:185], v[20:21]
	v_pk_fma_f32 v[104:105], v[62:63], v[184:185], v[14:15]
	v_pk_fma_f32 v[108:109], v[8:9], v[186:187], v[22:23]
	v_pk_fma_f32 v[102:103], v[64:65], v[186:187], v[16:17]
	s_waitcnt lgkmcnt(0)
	v_pk_fma_f32 v[106:107], v[2:3], v[188:189], v[24:25]
	v_pk_fma_f32 v[100:101], v[58:59], v[188:189], v[10:11]
	v_pk_fma_f32 v[112:113], v[4:5], v[190:191], v[18:19]
	v_pk_add_f32 v[34:35], v[12:13], v[128:129] op_sel:[0,1] op_sel_hi:[1,0]
	ds_read_b128 v[14:17], v127
	ds_read_b128 v[10:13], v127 offset:16
	v_mov_b32_e32 v116, v35
	v_mov_b32_e32 v117, v34
	ds_read_b128 v[22:25], v127 offset:2048
	ds_read_b128 v[18:21], v127 offset:2064
	ds_read_b128 v[30:33], v127 offset:4096
	ds_read_b128 v[26:29], v127 offset:4112
	ds_read_b128 v[38:41], v127 offset:6144
	ds_read_b128 v[34:37], v127 offset:6160
	ds_read_b128 v[46:49], v127 offset:8192
	ds_read_b128 v[42:45], v127 offset:8208
	ds_read_b128 v[54:57], v127 offset:10240
	ds_read_b128 v[50:53], v127 offset:10256
	ds_read_b128 v[62:65], v127 offset:12288
	ds_read_b128 v[58:61], v127 offset:12304
	s_cmp_lg_u32 s10, 0
	s_cbranch_scc1 .Lp4_c3_l1
; __device__ void conv_phase(LAS unsigned char* lds, const Params& p) {
;     ...
;                 for (int q = 0; q < 8; ++q) {
;                     const int xx = base - 15 + hb * 8 + q;
;                     const int xc = min(max(xx, 0), 63);
;                     const u32x4 r = *(const u32x4*)(Pb + (offb + (unsigned)xc * stepB));
;                     const bool ok = (xx == xc);
;                     raw[q] = (u32x4){ok ? r[0] : 0u, ok ? r[1] : 0u, ok ? r[2] : 0u, ok ? r[3] : 0u};
;                 }
	s_waitcnt vmcnt(15)
	v_cndmask_b32_e64 v160, 0, v224, s[42:43]
	v_cndmask_b32_e64 v161, 0, v225, s[42:43]
	v_cndmask_b32_e64 v162, 0, v226, s[42:43]
	v_cndmask_b32_e64 v163, 0, v227, s[42:43]
	s_waitcnt vmcnt(14)
	v_cndmask_b32_e64 v164, 0, v228, s[44:45]
	v_cndmask_b32_e64 v165, 0, v229, s[44:45]
	v_cndmask_b32_e64 v166, 0, v230, s[44:45]
	v_cndmask_b32_e64 v167, 0, v231, s[44:45]
	s_waitcnt vmcnt(13)
	v_cndmask_b32_e64 v168, 0, v232, s[46:47]
	v_cndmask_b32_e64 v169, 0, v233, s[46:47]
	v_cndmask_b32_e64 v170, 0, v234, s[46:47]
	v_cndmask_b32_e64 v171, 0, v235, s[46:47]
	s_waitcnt vmcnt(12)
	v_cndmask_b32_e64 v172, 0, v236, s[50:51]
	v_cndmask_b32_e64 v173, 0, v237, s[50:51]
	v_cndmask_b32_e64 v174, 0, v238, s[50:51]
	v_cndmask_b32_e64 v175, 0, v239, s[50:51]
	s_waitcnt vmcnt(11)
	v_cndmask_b32_e64 v176, 0, v240, s[52:53]
	v_cndmask_b32_e64 v177, 0, v241, s[52:53]
	v_cndmask_b32_e64 v178, 0, v242, s[52:53]
	v_cndmask_b32_e64 v179, 0, v243, s[52:53]
	s_waitcnt vmcnt(10)
	v_cndmask_b32_e64 v180, 0, v244, s[64:65]
	v_cndmask_b32_e64 v181, 0, v245, s[64:65]
	v_cndmask_b32_e64 v182, 0, v246, s[64:65]
	v_cndmask_b32_e64 v183, 0, v247, s[64:65]
	s_waitcnt vmcnt(9)
	v_cndmask_b32_e64 v184, 0, v248, s[94:95]
	v_cndmask_b32_e64 v185, 0, v249, s[94:95]
	v_cndmask_b32_e64 v186, 0, v250, s[94:95]
	v_cndmask_b32_e64 v187, 0, v251, s[94:95]
	s_waitcnt vmcnt(8)
	v_cndmask_b32_e64 v188, 0, v252, s[96:97]
	v_cndmask_b32_e64 v189, 0, v253, s[96:97]
	v_cndmask_b32_e64 v190, 0, v254, s[96:97]
	v_cndmask_b32_e64 v191, 0, v255, s[96:97]
	s_branch .Lp4_c3_done
.Lp4_c3_l1:
	s_waitcnt vmcnt(7)
	v_cndmask_b32_e64 v160, 0, v224, s[42:43]
	v_cndmask_b32_e64 v161, 0, v225, s[42:43]
	v_cndmask_b32_e64 v162, 0, v226, s[42:43]
	v_cndmask_b32_e64 v163, 0, v227, s[42:43]
	s_waitcnt vmcnt(6)
	v_cndmask_b32_e64 v164, 0, v228, s[44:45]
	v_cndmask_b32_e64 v165, 0, v229, s[44:45]
	v_cndmask_b32_e64 v166, 0, v230, s[44:45]
	v_cndmask_b32_e64 v167, 0, v231, s[44:45]
	s_waitcnt vmcnt(5)
	v_cndmask_b32_e64 v168, 0, v232, s[46:47]
	v_cndmask_b32_e64 v169, 0, v233, s[46:47]
	v_cndmask_b32_e64 v170, 0, v234, s[46:47]
	v_cndmask_b32_e64 v171, 0, v235, s[46:47]
	s_waitcnt vmcnt(4)
	v_cndmask_b32_e64 v172, 0, v236, s[50:51]
	v_cndmask_b32_e64 v173, 0, v237, s[50:51]
	v_cndmask_b32_e64 v174, 0, v238, s[50:51]
	v_cndmask_b32_e64 v175, 0, v239, s[50:51]
	s_waitcnt vmcnt(3)
	v_cndmask_b32_e64 v176, 0, v240, s[52:53]
	v_cndmask_b32_e64 v177, 0, v241, s[52:53]
	v_cndmask_b32_e64 v178, 0, v242, s[52:53]
	v_cndmask_b32_e64 v179, 0, v243, s[52:53]
	s_waitcnt vmcnt(2)
	v_cndmask_b32_e64 v180, 0, v244, s[64:65]
	v_cndmask_b32_e64 v181, 0, v245, s[64:65]
	v_cndmask_b32_e64 v182, 0, v246, s[64:65]
	v_cndmask_b32_e64 v183, 0, v247, s[64:65]
	s_waitcnt vmcnt(1)
	v_cndmask_b32_e64 v184, 0, v248, s[94:95]
	v_cndmask_b32_e64 v185, 0, v249, s[94:95]
	v_cndmask_b32_e64 v186, 0, v250, s[94:95]
	v_cndmask_b32_e64 v187, 0, v251, s[94:95]
	s_waitcnt vmcnt(0)
	v_cndmask_b32_e64 v188, 0, v252, s[96:97]
	v_cndmask_b32_e64 v189, 0, v253, s[96:97]
	v_cndmask_b32_e64 v190, 0, v254, s[96:97]
	v_cndmask_b32_e64 v191, 0, v255, s[96:97]
.Lp4_c3_done:
	s_cmp_lg_u32 s10, 0
	s_cbranch_scc1 .Lp4_nopf_3
	v_or_b32_e32 v225, 1, v124
	v_lshlrev_b32_e32 v225, 6, v225
	v_or_b32_e32 v226, 1, v123
	v_cndmask_b32_e64 v226, v226, v225, s[6:7]
	v_lshl_or_b32 v227, v226, 10, v125
	v_add_u32_e32 v225, -7, v115
	v_med3_i32 v226, v225, 0, 63
	v_cmp_eq_u32_e64 s[42:43], v225, v226
	v_lshl_add_u32 v224, v226, v118, v227
	v_add_u32_e32 v229, -6, v115
	v_med3_i32 v230, v229, 0, 63
	v_cmp_eq_u32_e64 s[44:45], v229, v230
	v_lshl_add_u32 v228, v230, v118, v227
	v_add_u32_e32 v233, -5, v115
	v_med3_i32 v234, v233, 0, 63
	v_cmp_eq_u32_e64 s[46:47], v233, v234
	v_lshl_add_u32 v232, v234, v118, v227
	v_add_u32_e32 v237, -4, v115
	v_med3_i32 v238, v237, 0, 63
	v_cmp_eq_u32_e64 s[50:51], v237, v238
	v_lshl_add_u32 v236, v238, v118, v227
	v_add_u32_e32 v241, -3, v115
	v_med3_i32 v242, v241, 0, 63
	v_cmp_eq_u32_e64 s[52:53], v241, v242
	v_lshl_add_u32 v240, v242, v118, v227
	v_add_u32_e32 v245, -2, v115
	v_med3_i32 v246, v245, 0, 63
	v_cmp_eq_u32_e64 s[64:65], v245, v246
	v_lshl_add_u32 v244, v246, v118, v227
	v_add_u32_e32 v249, -1, v115
	v_med3_i32 v250, v249, 0, 63
	v_cmp_eq_u32_e64 s[94:95], v249, v250
	v_lshl_add_u32 v248, v250, v118, v227
	v_add_u32_e32 v253, 0, v115
	v_med3_i32 v254, v253, 0, 63
	v_cmp_eq_u32_e64 s[96:97], v253, v254
	v_lshl_add_u32 v252, v254, v118, v227
	global_load_dwordx4 v[224:227], v224, s[26:27]
	s_nop 0
	global_load_dwordx4 v[228:231], v228, s[26:27]
	s_nop 0
	global_load_dwordx4 v[232:235], v232, s[26:27]
	s_nop 0
	global_load_dwordx4 v[236:239], v236, s[26:27]
	s_nop 0
	global_load_dwordx4 v[240:243], v240, s[26:27]
	s_nop 0
	global_load_dwordx4 v[244:247], v244, s[26:27]
	s_nop 0
	global_load_dwordx4 v[248:251], v248, s[26:27]
	s_nop 0
	global_load_dwordx4 v[252:255], v252, s[26:27]
; #define LAS __attribute__((address_space(3)))
; __device__ __forceinline__ float bf_lo(unsigned u) { return __uint_as_float(u << 16); }
; __device__ __forceinline__ float bf_hi(unsigned u) { return __uint_as_float(u & 0xffff0000u); }
; __device__ void conv_phase(LAS unsigned char* lds, const Params& p) {
;     ...
;                 for (int q = 0; q < 8; ++q) {
;                     const float in[8] = {bf_lo(raw[q][0]), bf_hi(raw[q][0]), bf_lo(raw[q][1]), bf_hi(raw[q][1]), bf_lo(raw[q][2]), bf_hi(raw[q][2]), bf_lo(raw[q][3]), bf_hi(raw[q][3])};
;                     const f32x4 wa = *(const LAS f32x4*)(wrow + q * 512), wb = *(const LAS f32x4*)(wrow + q * 512 + 4);
;                     const float Wc[8] = {wa[0], wa[1], wa[2], wa[3], wb[0], wb[1], wb[2], wb[3]};
; #pragma unroll
;                     for (int c = 0; c < 8; ++c) { cur[0][c] += Wc[c] * in[c]; cur[1][c] += Wp[c] * in[c]; Wp[c] = Wc[c]; }
;                 }
;             }
; #pragma unroll
;             for (int j = 0; j < 2; ++j)
; #pragma unroll
;                 for (int c = 0; c < 8; ++c) { if (line == 0) acc[j][c] = cur[j][c]; else acc[2 + j][c] = cur[j][c]; }
;         }
.Lp4_nopf_3:
	v_lshlrev_b32_e32 v128, 16, v160
	v_and_b32_e32 v129, 0xffff0000, v160
	v_lshlrev_b32_e32 v130, 16, v161
	v_and_b32_e32 v131, 0xffff0000, v161
	v_lshlrev_b32_e32 v132, 16, v162
	v_and_b32_e32 v133, 0xffff0000, v162
	v_lshlrev_b32_e32 v134, 16, v163
	v_and_b32_e32 v135, 0xffff0000, v163
	v_lshlrev_b32_e32 v136, 16, v164
	v_and_b32_e32 v137, 0xffff0000, v164
	v_lshlrev_b32_e32 v138, 16, v165
	v_and_b32_e32 v139, 0xffff0000, v165
	v_lshlrev_b32_e32 v140, 16, v166
	v_and_b32_e32 v141, 0xffff0000, v166
	v_lshlrev_b32_e32 v142, 16, v167
	v_and_b32_e32 v143, 0xffff0000, v167
	v_pk_fma_f32 v[104:105], v[6:7], v[128:129], v[104:105]
	v_pk_fma_f32 v[102:103], v[8:9], v[130:131], v[102:103]
	v_pk_fma_f32 v[100:101], v[2:3], v[132:133], v[100:101]
	v_pk_fma_f32 v[116:117], v[4:5], v[134:135], v[116:117]
	s_waitcnt lgkmcnt(12)
	v_pk_fma_f32 v[112:113], v[12:13], v[134:135], v[112:113]
	v_pk_fma_f32 v[110:111], v[14:15], v[128:129], v[110:111]
	v_pk_fma_f32 v[108:109], v[16:17], v[130:131], v[108:109]
	v_pk_fma_f32 v[106:107], v[10:11], v[132:133], v[106:107]
	v_lshlrev_b32_e32 v144, 16, v168
	v_and_b32_e32 v145, 0xffff0000, v168
	v_lshlrev_b32_e32 v146, 16, v169
	v_and_b32_e32 v147, 0xffff0000, v169
	v_lshlrev_b32_e32 v148, 16, v170
	v_and_b32_e32 v149, 0xffff0000, v170
	v_lshlrev_b32_e32 v150, 16, v171
	v_and_b32_e32 v151, 0xffff0000, v171
	v_pk_fma_f32 v[12:13], v[12:13], v[142:143], v[116:117]
	s_waitcnt lgkmcnt(10)
	v_pk_fma_f32 v[112:113], v[20:21], v[142:143], v[112:113]
	v_pk_fma_f32 v[110:111], v[22:23], v[136:137], v[110:111]
	v_pk_fma_f32 v[14:15], v[14:15], v[136:137], v[104:105]
	v_pk_fma_f32 v[104:105], v[24:25], v[138:139], v[108:109]
	v_pk_fma_f32 v[16:17], v[16:17], v[138:139], v[102:103]
	v_pk_fma_f32 v[102:103], v[18:19], v[140:141], v[106:107]
	v_pk_fma_f32 v[10:11], v[10:11], v[140:141], v[100:101]
	v_lshlrev_b32_e32 v152, 16, v172
	v_and_b32_e32 v153, 0xffff0000, v172
	v_lshlrev_b32_e32 v154, 16, v173
	v_and_b32_e32 v155, 0xffff0000, v173
	v_lshlrev_b32_e32 v156, 16, v174
	v_and_b32_e32 v157, 0xffff0000, v174
	v_lshlrev_b32_e32 v158, 16, v175
	v_and_b32_e32 v159, 0xffff0000, v175
	ds_read_b128 v[6:9], v127 offset:14336
	ds_read_b128 v[2:5], v127 offset:14352
	v_pk_fma_f32 v[12:13], v[20:21], v[150:151], v[12:13]
	s_waitcnt lgkmcnt(10)
	v_pk_fma_f32 v[20:21], v[28:29], v[150:151], v[112:113]
	v_pk_fma_f32 v[100:101], v[30:31], v[144:145], v[110:111]
	v_pk_fma_f32 v[14:15], v[22:23], v[144:145], v[14:15]
	v_pk_fma_f32 v[22:23], v[32:33], v[146:147], v[104:105]
	v_pk_fma_f32 v[16:17], v[24:25], v[146:147], v[16:17]
	v_pk_fma_f32 v[24:25], v[26:27], v[148:149], v[102:103]
	v_pk_fma_f32 v[10:11], v[18:19], v[148:149], v[10:11]
	v_lshlrev_b32_e32 v160, 16, v176
	v_and_b32_e32 v161, 0xffff0000, v176
	v_lshlrev_b32_e32 v162, 16, v177
	v_and_b32_e32 v163, 0xffff0000, v177
	v_lshlrev_b32_e32 v164, 16, v178
	v_and_b32_e32 v165, 0xffff0000, v178
	v_lshlrev_b32_e32 v166, 16, v179
	v_and_b32_e32 v167, 0xffff0000, v179
	v_pk_fma_f32 v[12:13], v[28:29], v[158:159], v[12:13]
	s_waitcnt lgkmcnt(8)
	v_pk_fma_f32 v[18:19], v[36:37], v[158:159], v[20:21]
	v_pk_fma_f32 v[20:21], v[38:39], v[152:153], v[100:101]
	v_pk_fma_f32 v[14:15], v[30:31], v[152:153], v[14:15]
	v_pk_fma_f32 v[22:23], v[40:41], v[154:155], v[22:23]
	v_pk_fma_f32 v[16:17], v[32:33], v[154:155], v[16:17]
	v_pk_fma_f32 v[24:25], v[34:35], v[156:157], v[24:25]
	v_pk_fma_f32 v[10:11], v[26:27], v[156:157], v[10:11]
	v_lshlrev_b32_e32 v168, 16, v180
	v_and_b32_e32 v169, 0xffff0000, v180
	v_lshlrev_b32_e32 v170, 16, v181
	v_and_b32_e32 v171, 0xffff0000, v181
	v_lshlrev_b32_e32 v172, 16, v182
	v_and_b32_e32 v173, 0xffff0000, v182
	v_lshlrev_b32_e32 v174, 16, v183
	v_and_b32_e32 v175, 0xffff0000, v183
	v_pk_fma_f32 v[12:13], v[36:37], v[166:167], v[12:13]
	s_waitcnt lgkmcnt(6)
	v_pk_fma_f32 v[18:19], v[44:45], v[166:167], v[18:19]
	v_pk_fma_f32 v[20:21], v[46:47], v[160:161], v[20:21]
	v_pk_fma_f32 v[14:15], v[38:39], v[160:161], v[14:15]
	v_pk_fma_f32 v[22:23], v[48:49], v[162:163], v[22:23]
	v_pk_fma_f32 v[16:17], v[40:41], v[162:163], v[16:17]
	v_pk_fma_f32 v[24:25], v[42:43], v[164:165], v[24:25]
	v_pk_fma_f32 v[10:11], v[34:35], v[164:165], v[10:11]
	v_lshlrev_b32_e32 v176, 16, v184
	v_and_b32_e32 v177, 0xffff0000, v184
	v_lshlrev_b32_e32 v178, 16, v185
	v_and_b32_e32 v179, 0xffff0000, v185
	v_lshlrev_b32_e32 v180, 16, v186
	v_and_b32_e32 v181, 0xffff0000, v186
	v_lshlrev_b32_e32 v183, 16, v187
	v_and_b32_e32 v182, 0xffff0000, v187
	v_lshlrev_b32_e32 v184, 16, v188
	v_and_b32_e32 v185, 0xffff0000, v188
	v_lshlrev_b32_e32 v186, 16, v189
	v_and_b32_e32 v187, 0xffff0000, v189
	v_lshlrev_b32_e32 v188, 16, v190
	v_and_b32_e32 v189, 0xffff0000, v190
	v_lshlrev_b32_e32 v190, 16, v191
	v_and_b32_e32 v191, 0xffff0000, v191
	v_pk_fma_f32 v[12:13], v[44:45], v[174:175], v[12:13]
	s_waitcnt lgkmcnt(4)
	v_pk_fma_f32 v[18:19], v[52:53], v[174:175], v[18:19]
	v_pk_fma_f32 v[20:21], v[54:55], v[168:169], v[20:21]
	v_pk_fma_f32 v[14:15], v[46:47], v[168:169], v[14:15]
	v_pk_fma_f32 v[22:23], v[56:57], v[170:171], v[22:23]
	v_pk_fma_f32 v[16:17], v[48:49], v[170:171], v[16:17]
	v_pk_fma_f32 v[24:25], v[50:51], v[172:173], v[24:25]
	v_pk_fma_f32 v[10:11], v[42:43], v[172:173], v[10:11]
	s_waitcnt lgkmcnt(2)
	v_pk_mul_f32 v[128:129], v[60:61], v[190:191]
	v_pk_fma_f32 v[18:19], v[60:61], v[182:183], v[18:19] op_sel:[0,1,0] op_sel_hi:[1,0,1]
	v_pk_fma_f32 v[20:21], v[62:63], v[176:177], v[20:21]
	v_pk_fma_f32 v[14:15], v[54:55], v[176:177], v[14:15]
	v_pk_fma_f32 v[22:23], v[64:65], v[178:179], v[22:23]
	v_pk_fma_f32 v[16:17], v[56:57], v[178:179], v[16:17]
	v_pk_fma_f32 v[24:25], v[58:59], v[180:181], v[24:25]
	v_pk_fma_f32 v[10:11], v[50:51], v[180:181], v[10:11]
	v_pk_fma_f32 v[12:13], v[52:53], v[182:183], v[12:13] op_sel:[1,0,1] op_sel_hi:[0,1,0]
	v_add_u32_e32 v127, 0x4000, v127
	s_waitcnt lgkmcnt(1)
	v_pk_fma_f32 v[110:111], v[6:7], v[184:185], v[20:21]
	v_pk_fma_f32 v[104:105], v[62:63], v[184:185], v[14:15]
	v_pk_fma_f32 v[108:109], v[8:9], v[186:187], v[22:23]
	v_pk_fma_f32 v[102:103], v[64:65], v[186:187], v[16:17]
	s_waitcnt lgkmcnt(0)
	v_pk_fma_f32 v[106:107], v[2:3], v[188:189], v[24:25]
	v_pk_fma_f32 v[100:101], v[58:59], v[188:189], v[10:11]
	v_pk_fma_f32 v[112:113], v[4:5], v[190:191], v[18:19]
	v_pk_add_f32 v[34:35], v[12:13], v[128:129] op_sel:[0,1] op_sel_hi:[1,0]
	s_mov_b32 s10, 1
	s_mov_b64 s[8:9], 0
	s_and_b64 vcc, exec, s[38:39]
	s_cbranch_vccnz .LBB0_371
	v_mov_b32_e32 v121, v34
	v_mov_b32_e32 v122, v35
	v_mov_b64_e32 v[86:87], v[106:107]
	v_mov_b64_e32 v[90:91], v[108:109]
	v_mov_b64_e32 v[92:93], v[110:111]
	v_mov_b64_e32 v[94:95], v[100:101]
	v_mov_b64_e32 v[96:97], v[102:103]
	v_mov_b64_e32 v[98:99], v[104:105]
	v_mov_b32_e32 v88, v113
	v_mov_b32_e32 v89, v112
	s_branch .LBB0_373
